# tok0_mem score pass: memory-row loads double-buffered one pass ahead, 8 wave reductions per pass interleaved (both token-0 side chains)
# baseline (speedup 1.0000x reference)
; DI void tok0_mem(ldsp lds, const float* qm, const float* memb, const float* mnw, const float* Wkv, int hm, LAS float* out64, int tid, int wid, int lane) {
;     ...
;         for (int i0 = 0; i0 < 32; i0 += 4) {
;             float4 m4[4][4];
; #pragma unroll
;             for (int r = 0; r < 4; ++r) { const float* mr = memb + (size_t)(wid * 32 + i0 + r) * 1024;
; #pragma unroll
;                 for (int q = 0; q < 4; ++q) m4[r][q] = *(const float4*)(mr + q * 256 + lane * 4); }
; #pragma unroll
;             for (int r = 0; r < 4; ++r) {
;                 const int n = wid * 32 + i0 + r; float dd = 0.f, ss = 0.f;
; #pragma unroll
;                 for (int q = 0; q < 4; ++q) { const float4 m = m4[r][q];
;                     dd += m.x * u4[q][0] + m.y * u4[q][1] + m.z * u4[q][2] + m.w * u4[q][3]; ss += m.x * m.x + m.y * m.y + m.z * m.z + m.w * m.w; }
;                 dd = wave_sum(dd); ss = wave_sum(ss);
.Lp2_entry_s5:
	s_movk_i32 s22, 0xf000
	v_add_co_u32_e32 v248, vcc, 0xffffd000, v92
	s_nop 1
	v_addc_co_u32_e32 v249, vcc, -1, v93, vcc
	global_load_dwordx4 v[110:113], v[248:249], off offset:-3084
	global_load_dwordx4 v[114:117], v[248:249], off offset:-2060
	global_load_dwordx4 v[74:77], v[248:249], off offset:-1036
	global_load_dwordx4 v[70:73], v[248:249], off offset:-12
	v_add_co_u32_e32 v248, vcc, s21, v92
	s_nop 1
	v_addc_co_u32_e32 v249, vcc, -1, v93, vcc
	global_load_dwordx4 v[66:69], v[248:249], off offset:-3084
	global_load_dwordx4 v[62:65], v[248:249], off offset:-2060
	global_load_dwordx4 v[58:61], v[248:249], off offset:-1036
	global_load_dwordx4 v[54:57], v[248:249], off offset:-12
	v_add_co_u32_e32 v248, vcc, s22, v92
	s_nop 1
	v_addc_co_u32_e32 v249, vcc, -1, v93, vcc
	global_load_dwordx4 v[50:53], v[248:249], off offset:-3084
	global_load_dwordx4 v[46:49], v[248:249], off offset:-2060
	global_load_dwordx4 v[42:45], v[248:249], off offset:-1036
	global_load_dwordx4 v[38:41], v[248:249], off offset:-12
	global_load_dwordx4 v[34:37], v[92:93], off offset:-3084
	global_load_dwordx4 v[26:29], v[92:93], off offset:-2060
	global_load_dwordx4 v[22:25], v[92:93], off offset:-1036
	global_load_dwordx4 v[18:21], v[92:93], off offset:-12
.LBB0_100:
	v_lshl_add_u64 v[246:247], v[92:93], 0, s[24:25]
	s_movk_i32 s22, 0xf000
	v_add_co_u32_e32 v248, vcc, 0xffffd000, v246
	s_nop 1
	v_addc_co_u32_e32 v249, vcc, -1, v247, vcc
	global_load_dwordx4 v[158:161], v[248:249], off offset:-3084
	global_load_dwordx4 v[162:165], v[248:249], off offset:-2060
	global_load_dwordx4 v[166:169], v[248:249], off offset:-1036
	global_load_dwordx4 v[170:173], v[248:249], off offset:-12
	v_add_co_u32_e32 v248, vcc, s21, v246
	s_nop 1
	v_addc_co_u32_e32 v249, vcc, -1, v247, vcc
	global_load_dwordx4 v[174:177], v[248:249], off offset:-3084
	global_load_dwordx4 v[178:181], v[248:249], off offset:-2060
	global_load_dwordx4 v[182:185], v[248:249], off offset:-1036
	global_load_dwordx4 v[186:189], v[248:249], off offset:-12
	v_add_co_u32_e32 v248, vcc, s22, v246
	s_nop 1
	v_addc_co_u32_e32 v249, vcc, -1, v247, vcc
	global_load_dwordx4 v[190:193], v[248:249], off offset:-3084
	global_load_dwordx4 v[194:197], v[248:249], off offset:-2060
	global_load_dwordx4 v[198:201], v[248:249], off offset:-1036
	global_load_dwordx4 v[202:205], v[248:249], off offset:-12
	global_load_dwordx4 v[206:209], v[246:247], off offset:-3084
	global_load_dwordx4 v[210:213], v[246:247], off offset:-2060
	global_load_dwordx4 v[214:217], v[246:247], off offset:-1036
	global_load_dwordx4 v[218:221], v[246:247], off offset:-12
	s_waitcnt vmcnt(16) lgkmcnt(0)
	v_mul_f32_e32 v132, v1, v111
	v_mul_f32_e32 v133, v1, v67
	v_mul_f32_e32 v134, v1, v51
	v_mul_f32_e32 v135, v1, v35
	v_mul_f32_e32 v152, v111, v111
	v_mul_f32_e32 v153, v67, v67
	v_mul_f32_e32 v222, v51, v51
	v_mul_f32_e32 v223, v35, v35
	v_fmac_f32_e32 v132, v0, v110
	v_fmac_f32_e32 v133, v0, v66
	v_fmac_f32_e32 v134, v0, v50
	v_fmac_f32_e32 v135, v0, v34
	v_fmac_f32_e32 v152, v110, v110
	v_fmac_f32_e32 v153, v66, v66
	v_fmac_f32_e32 v222, v50, v50
	v_fmac_f32_e32 v223, v34, v34
	v_fmac_f32_e32 v132, v2, v112
	v_fmac_f32_e32 v133, v2, v68
	v_fmac_f32_e32 v134, v2, v52
	v_fmac_f32_e32 v135, v2, v36
	v_fmac_f32_e32 v152, v112, v112
	v_fmac_f32_e32 v153, v68, v68
	v_fmac_f32_e32 v222, v52, v52
	v_fmac_f32_e32 v223, v36, v36
	v_fmac_f32_e32 v132, v3, v113
	v_fmac_f32_e32 v133, v3, v69
	v_fmac_f32_e32 v134, v3, v53
	v_fmac_f32_e32 v135, v3, v37
	v_fmac_f32_e32 v152, v113, v113
	v_fmac_f32_e32 v153, v69, v69
	v_fmac_f32_e32 v222, v53, v53
	v_fmac_f32_e32 v223, v37, v37
	v_add_f32_e32 v124, 0, v132
	v_add_f32_e32 v125, 0, v133
	v_add_f32_e32 v126, 0, v134
	v_add_f32_e32 v127, 0, v135
	v_mov_b32_e32 v128, v152
	v_mov_b32_e32 v129, v153
	v_mov_b32_e32 v130, v222
	v_mov_b32_e32 v131, v223
	v_mul_f32_e32 v132, v5, v115
	v_mul_f32_e32 v133, v5, v63
	v_mul_f32_e32 v134, v5, v47
	v_mul_f32_e32 v135, v5, v27
	v_mul_f32_e32 v152, v115, v115
	v_mul_f32_e32 v153, v63, v63
	v_mul_f32_e32 v222, v47, v47
	v_mul_f32_e32 v223, v27, v27
	v_fmac_f32_e32 v132, v4, v114
	v_fmac_f32_e32 v133, v4, v62
	v_fmac_f32_e32 v134, v4, v46
	v_fmac_f32_e32 v135, v4, v26
	v_fmac_f32_e32 v152, v114, v114
	v_fmac_f32_e32 v153, v62, v62
	v_fmac_f32_e32 v222, v46, v46
	v_fmac_f32_e32 v223, v26, v26
	v_fmac_f32_e32 v132, v6, v116
	v_fmac_f32_e32 v133, v6, v64
	v_fmac_f32_e32 v134, v6, v48
	v_fmac_f32_e32 v135, v6, v28
	v_fmac_f32_e32 v152, v116, v116
	v_fmac_f32_e32 v153, v64, v64
	v_fmac_f32_e32 v222, v48, v48
	v_fmac_f32_e32 v223, v28, v28
	v_fmac_f32_e32 v132, v7, v117
	v_fmac_f32_e32 v133, v7, v65
	v_fmac_f32_e32 v134, v7, v49
	v_fmac_f32_e32 v135, v7, v29
	v_fmac_f32_e32 v152, v117, v117
	v_fmac_f32_e32 v153, v65, v65
	v_fmac_f32_e32 v222, v49, v49
	v_fmac_f32_e32 v223, v29, v29
	v_add_f32_e32 v124, v124, v132
	v_add_f32_e32 v125, v125, v133
	v_add_f32_e32 v126, v126, v134
	v_add_f32_e32 v127, v127, v135
	v_add_f32_e32 v128, v128, v152
	v_add_f32_e32 v129, v129, v153
	v_add_f32_e32 v130, v130, v222
	v_add_f32_e32 v131, v131, v223
	v_mul_f32_e32 v132, v9, v75
	v_mul_f32_e32 v133, v9, v59
	v_mul_f32_e32 v134, v9, v43
	v_mul_f32_e32 v135, v9, v23
	v_mul_f32_e32 v152, v75, v75
	v_mul_f32_e32 v153, v59, v59
	v_mul_f32_e32 v222, v43, v43
	v_mul_f32_e32 v223, v23, v23
	v_fmac_f32_e32 v132, v8, v74
	v_fmac_f32_e32 v133, v8, v58
	v_fmac_f32_e32 v134, v8, v42
	v_fmac_f32_e32 v135, v8, v22
	v_fmac_f32_e32 v152, v74, v74
	v_fmac_f32_e32 v153, v58, v58
	v_fmac_f32_e32 v222, v42, v42
	v_fmac_f32_e32 v223, v22, v22
	v_fmac_f32_e32 v132, v10, v76
	v_fmac_f32_e32 v133, v10, v60
; DI void tok0_mem(ldsp lds, const float* qm, const float* memb, const float* mnw, const float* Wkv, int hm, LAS float* out64, int tid, int wid, int lane) {
;     ...
;                 for (int q = 0; q < 4; ++q) { const float4 m = m4[r][q];
;                     dd += m.x * u4[q][0] + m.y * u4[q][1] + m.z * u4[q][2] + m.w * u4[q][3]; ss += m.x * m.x + m.y * m.y + m.z * m.z + m.w * m.w; }
;                 dd = wave_sum(dd); ss = wave_sum(ss);
	v_fmac_f32_e32 v134, v10, v44
	v_fmac_f32_e32 v135, v10, v24
	v_fmac_f32_e32 v152, v76, v76
	v_fmac_f32_e32 v153, v60, v60
	v_fmac_f32_e32 v222, v44, v44
	v_fmac_f32_e32 v223, v24, v24
	v_fmac_f32_e32 v132, v11, v77
	v_fmac_f32_e32 v133, v11, v61
	v_fmac_f32_e32 v134, v11, v45
	v_fmac_f32_e32 v135, v11, v25
	v_fmac_f32_e32 v152, v77, v77
	v_fmac_f32_e32 v153, v61, v61
	v_fmac_f32_e32 v222, v45, v45
	v_fmac_f32_e32 v223, v25, v25
	v_add_f32_e32 v124, v124, v132
	v_add_f32_e32 v125, v125, v133
	v_add_f32_e32 v126, v126, v134
	v_add_f32_e32 v127, v127, v135
	v_add_f32_e32 v128, v128, v152
	v_add_f32_e32 v129, v129, v153
	v_add_f32_e32 v130, v130, v222
	v_add_f32_e32 v131, v131, v223
	v_mul_f32_e32 v132, v15, v71
	v_mul_f32_e32 v133, v15, v55
	v_mul_f32_e32 v134, v15, v39
	v_mul_f32_e32 v135, v15, v19
	v_mul_f32_e32 v152, v71, v71
	v_mul_f32_e32 v153, v55, v55
	v_mul_f32_e32 v222, v39, v39
	v_mul_f32_e32 v223, v19, v19
	v_fmac_f32_e32 v132, v14, v70
	v_fmac_f32_e32 v133, v14, v54
	v_fmac_f32_e32 v134, v14, v38
	v_fmac_f32_e32 v135, v14, v18
	v_fmac_f32_e32 v152, v70, v70
	v_fmac_f32_e32 v153, v54, v54
	v_fmac_f32_e32 v222, v38, v38
	v_fmac_f32_e32 v223, v18, v18
	v_fmac_f32_e32 v132, v16, v72
	v_fmac_f32_e32 v133, v16, v56
	v_fmac_f32_e32 v134, v16, v40
	v_fmac_f32_e32 v135, v16, v20
	v_fmac_f32_e32 v152, v72, v72
	v_fmac_f32_e32 v153, v56, v56
	v_fmac_f32_e32 v222, v40, v40
	v_fmac_f32_e32 v223, v20, v20
	v_fmac_f32_e32 v132, v17, v73
	v_fmac_f32_e32 v133, v17, v57
	v_fmac_f32_e32 v134, v17, v41
	v_fmac_f32_e32 v135, v17, v21
	v_fmac_f32_e32 v152, v73, v73
	v_fmac_f32_e32 v153, v57, v57
	v_fmac_f32_e32 v222, v41, v41
	v_fmac_f32_e32 v223, v21, v21
	v_add_f32_e32 v124, v124, v132
	v_add_f32_e32 v125, v125, v133
	v_add_f32_e32 v126, v126, v134
	v_add_f32_e32 v127, v127, v135
	v_add_f32_e32 v128, v128, v152
	v_add_f32_e32 v129, v129, v153
	v_add_f32_e32 v130, v130, v222
	v_add_f32_e32 v131, v131, v223
	ds_bpermute_b32 v132, v95, v124
	ds_bpermute_b32 v133, v95, v125
	ds_bpermute_b32 v134, v95, v126
	ds_bpermute_b32 v135, v95, v127
	ds_bpermute_b32 v152, v95, v128
	ds_bpermute_b32 v153, v95, v129
	ds_bpermute_b32 v222, v95, v130
	ds_bpermute_b32 v223, v95, v131
	s_waitcnt lgkmcnt(7)
	v_add_f32_e32 v124, v124, v132
	s_waitcnt lgkmcnt(6)
	v_add_f32_e32 v125, v125, v133
	s_waitcnt lgkmcnt(5)
	v_add_f32_e32 v126, v126, v134
	s_waitcnt lgkmcnt(4)
	v_add_f32_e32 v127, v127, v135
	s_waitcnt lgkmcnt(3)
	v_add_f32_e32 v128, v128, v152
	s_waitcnt lgkmcnt(2)
	v_add_f32_e32 v129, v129, v153
	s_waitcnt lgkmcnt(1)
	v_add_f32_e32 v130, v130, v222
	s_waitcnt lgkmcnt(0)
	v_add_f32_e32 v131, v131, v223
	ds_bpermute_b32 v132, v96, v124
	ds_bpermute_b32 v133, v96, v125
	ds_bpermute_b32 v134, v96, v126
	ds_bpermute_b32 v135, v96, v127
	ds_bpermute_b32 v152, v96, v128
	ds_bpermute_b32 v153, v96, v129
	ds_bpermute_b32 v222, v96, v130
	ds_bpermute_b32 v223, v96, v131
	s_waitcnt lgkmcnt(7)
	v_add_f32_e32 v124, v124, v132
	s_waitcnt lgkmcnt(6)
	v_add_f32_e32 v125, v125, v133
	s_waitcnt lgkmcnt(5)
	v_add_f32_e32 v126, v126, v134
	s_waitcnt lgkmcnt(4)
	v_add_f32_e32 v127, v127, v135
	s_waitcnt lgkmcnt(3)
	v_add_f32_e32 v128, v128, v152
	s_waitcnt lgkmcnt(2)
	v_add_f32_e32 v129, v129, v153
	s_waitcnt lgkmcnt(1)
	v_add_f32_e32 v130, v130, v222
	s_waitcnt lgkmcnt(0)
	v_add_f32_e32 v131, v131, v223
	ds_bpermute_b32 v132, v97, v124
	ds_bpermute_b32 v133, v97, v125
	ds_bpermute_b32 v134, v97, v126
	ds_bpermute_b32 v135, v97, v127
	ds_bpermute_b32 v152, v97, v128
	ds_bpermute_b32 v153, v97, v129
	ds_bpermute_b32 v222, v97, v130
	ds_bpermute_b32 v223, v97, v131
	s_waitcnt lgkmcnt(7)
	v_add_f32_e32 v124, v124, v132
	s_waitcnt lgkmcnt(6)
	v_add_f32_e32 v125, v125, v133
	s_waitcnt lgkmcnt(5)
	v_add_f32_e32 v126, v126, v134
	s_waitcnt lgkmcnt(4)
	v_add_f32_e32 v127, v127, v135
	s_waitcnt lgkmcnt(3)
	v_add_f32_e32 v128, v128, v152
	s_waitcnt lgkmcnt(2)
	v_add_f32_e32 v129, v129, v153
	s_waitcnt lgkmcnt(1)
	v_add_f32_e32 v130, v130, v222
	s_waitcnt lgkmcnt(0)
	v_add_f32_e32 v131, v131, v223
	ds_bpermute_b32 v132, v98, v124
	ds_bpermute_b32 v133, v98, v125
	ds_bpermute_b32 v134, v98, v126
	ds_bpermute_b32 v135, v98, v127
	ds_bpermute_b32 v152, v98, v128
	ds_bpermute_b32 v153, v98, v129
	ds_bpermute_b32 v222, v98, v130
	ds_bpermute_b32 v223, v98, v131
	s_waitcnt lgkmcnt(7)
	v_add_f32_e32 v124, v124, v132
	s_waitcnt lgkmcnt(6)
	v_add_f32_e32 v125, v125, v133
	s_waitcnt lgkmcnt(5)
	v_add_f32_e32 v126, v126, v134
	s_waitcnt lgkmcnt(4)
	v_add_f32_e32 v127, v127, v135
	s_waitcnt lgkmcnt(3)
	v_add_f32_e32 v128, v128, v152
	s_waitcnt lgkmcnt(2)
	v_add_f32_e32 v129, v129, v153
	s_waitcnt lgkmcnt(1)
; DI void tok0_mem(ldsp lds, const float* qm, const float* memb, const float* mnw, const float* Wkv, int hm, LAS float* out64, int tid, int wid, int lane) {
;     ...
;                 dd = wave_sum(dd); ss = wave_sum(ss);
;                 if (lane == 0) { const float rstd = rsqrtf(ss * (1.0f / 1024.0f) + 1e-6f); SC[n] = dd * rstd * 0.125f; RSN[n] = rstd; }
;             }
	v_add_f32_e32 v130, v130, v222
	s_waitcnt lgkmcnt(0)
	v_add_f32_e32 v131, v131, v223
	ds_bpermute_b32 v132, v99, v124
	ds_bpermute_b32 v133, v99, v125
	ds_bpermute_b32 v134, v99, v126
	ds_bpermute_b32 v135, v99, v127
	ds_bpermute_b32 v152, v99, v128
	ds_bpermute_b32 v153, v99, v129
	ds_bpermute_b32 v222, v99, v130
	ds_bpermute_b32 v223, v99, v131
	s_waitcnt lgkmcnt(7)
	v_add_f32_e32 v124, v124, v132
	s_waitcnt lgkmcnt(6)
	v_add_f32_e32 v125, v125, v133
	s_waitcnt lgkmcnt(5)
	v_add_f32_e32 v126, v126, v134
	s_waitcnt lgkmcnt(4)
	v_add_f32_e32 v127, v127, v135
	s_waitcnt lgkmcnt(3)
	v_add_f32_e32 v128, v128, v152
	s_waitcnt lgkmcnt(2)
	v_add_f32_e32 v129, v129, v153
	s_waitcnt lgkmcnt(1)
	v_add_f32_e32 v130, v130, v222
	s_waitcnt lgkmcnt(0)
	v_add_f32_e32 v131, v131, v223
	ds_bpermute_b32 v132, v100, v124
	ds_bpermute_b32 v133, v100, v125
	ds_bpermute_b32 v134, v100, v126
	ds_bpermute_b32 v135, v100, v127
	ds_bpermute_b32 v152, v100, v128
	ds_bpermute_b32 v153, v100, v129
	ds_bpermute_b32 v222, v100, v130
	ds_bpermute_b32 v223, v100, v131
	s_waitcnt lgkmcnt(7)
	v_add_f32_e32 v124, v124, v132
	s_waitcnt lgkmcnt(6)
	v_add_f32_e32 v125, v125, v133
	s_waitcnt lgkmcnt(5)
	v_add_f32_e32 v126, v126, v134
	s_waitcnt lgkmcnt(4)
	v_add_f32_e32 v127, v127, v135
	s_waitcnt lgkmcnt(3)
	v_add_f32_e32 v128, v128, v152
	s_waitcnt lgkmcnt(2)
	v_add_f32_e32 v129, v129, v153
	s_waitcnt lgkmcnt(1)
	v_add_f32_e32 v130, v130, v222
	s_waitcnt lgkmcnt(0)
	v_add_f32_e32 v131, v131, v223
	s_and_saveexec_b64 s[22:23], s[40:41]
	v_fmamk_f32 v128, v128, 0x3a800000, v231
	v_mul_f32_e32 v132, 0x4b800000, v128
	v_cmp_gt_f32_e32 vcc, s33, v128
	s_nop 1
	v_cndmask_b32_e32 v128, v128, v132, vcc
	v_rsq_f32_e32 v128, v128
	s_nop 0
	v_mul_f32_e32 v132, 0x45800000, v128
	v_cndmask_b32_e32 v132, v128, v132, vcc
	v_mul_f32_e32 v124, v124, v132
	v_mul_f32_e32 v124, 0x3e000000, v124
	v_mov_b32_e32 v152, s30
	ds_write2st64_b32 v152, v124, v132 offset1:4
	v_fmamk_f32 v129, v129, 0x3a800000, v231
	v_mul_f32_e32 v133, 0x4b800000, v129
	v_cmp_gt_f32_e32 vcc, s33, v129
	s_nop 1
	v_cndmask_b32_e32 v129, v129, v133, vcc
	v_rsq_f32_e32 v129, v129
	s_nop 0
	v_mul_f32_e32 v133, 0x45800000, v129
	v_cndmask_b32_e32 v133, v129, v133, vcc
	v_mul_f32_e32 v125, v125, v133
	v_mul_f32_e32 v125, 0x3e000000, v125
	v_add_u32_e64 v153, 4, s30
	ds_write2st64_b32 v153, v125, v133 offset1:4
	v_fmamk_f32 v130, v130, 0x3a800000, v231
	v_mul_f32_e32 v134, 0x4b800000, v130
	v_cmp_gt_f32_e32 vcc, s33, v130
	s_nop 1
	v_cndmask_b32_e32 v130, v130, v134, vcc
	v_rsq_f32_e32 v130, v130
	s_nop 0
	v_mul_f32_e32 v134, 0x45800000, v130
	v_cndmask_b32_e32 v134, v130, v134, vcc
	v_mul_f32_e32 v126, v126, v134
	v_mul_f32_e32 v126, 0x3e000000, v126
	v_add_u32_e64 v222, 8, s30
	ds_write2st64_b32 v222, v126, v134 offset1:4
	v_fmamk_f32 v131, v131, 0x3a800000, v231
	v_mul_f32_e32 v135, 0x4b800000, v131
	v_cmp_gt_f32_e32 vcc, s33, v131
	s_nop 1
	v_cndmask_b32_e32 v131, v131, v135, vcc
	v_rsq_f32_e32 v131, v131
	s_nop 0
	v_mul_f32_e32 v135, 0x45800000, v131
	v_cndmask_b32_e32 v135, v131, v135, vcc
	v_mul_f32_e32 v127, v127, v135
	v_mul_f32_e32 v127, 0x3e000000, v127
	v_add_u32_e64 v223, 12, s30
	ds_write2st64_b32 v223, v127, v135 offset1:4
	s_or_b64 exec, exec, s[22:23]
	v_lshl_add_u64 v[92:93], v[246:247], 0, s[24:25]
	s_cmp_gt_i32 s0, 19
	s_cbranch_scc1 .Lp2_last_s5
	s_movk_i32 s22, 0xf000
	v_add_co_u32_e32 v248, vcc, 0xffffd000, v92
	s_nop 1
	v_addc_co_u32_e32 v249, vcc, -1, v93, vcc
	global_load_dwordx4 v[110:113], v[248:249], off offset:-3084
	global_load_dwordx4 v[114:117], v[248:249], off offset:-2060
	global_load_dwordx4 v[74:77], v[248:249], off offset:-1036
	global_load_dwordx4 v[70:73], v[248:249], off offset:-12
	v_add_co_u32_e32 v248, vcc, s21, v92
	s_nop 1
	v_addc_co_u32_e32 v249, vcc, -1, v93, vcc
	global_load_dwordx4 v[66:69], v[248:249], off offset:-3084
	global_load_dwordx4 v[62:65], v[248:249], off offset:-2060
	global_load_dwordx4 v[58:61], v[248:249], off offset:-1036
	global_load_dwordx4 v[54:57], v[248:249], off offset:-12
	v_add_co_u32_e32 v248, vcc, s22, v92
	s_nop 1
	v_addc_co_u32_e32 v249, vcc, -1, v93, vcc
	global_load_dwordx4 v[50:53], v[248:249], off offset:-3084
	global_load_dwordx4 v[46:49], v[248:249], off offset:-2060
	global_load_dwordx4 v[42:45], v[248:249], off offset:-1036
	global_load_dwordx4 v[38:41], v[248:249], off offset:-12
	global_load_dwordx4 v[34:37], v[92:93], off offset:-3084
	global_load_dwordx4 v[26:29], v[92:93], off offset:-2060
	global_load_dwordx4 v[22:25], v[92:93], off offset:-1036
	global_load_dwordx4 v[18:21], v[92:93], off offset:-12
	s_waitcnt vmcnt(16)
	s_branch .Lp2_procb_s5

; DI void tok0_mem(ldsp lds, const float* qm, const float* memb, const float* mnw, const float* Wkv, int hm, LAS float* out64, int tid, int wid, int lane) {
;     ...
;             for (int r = 0; r < 4; ++r) {
;                 const int n = wid * 32 + i0 + r; float dd = 0.f, ss = 0.f;
; #pragma unroll
;                 for (int q = 0; q < 4; ++q) { const float4 m = m4[r][q];
;                     dd += m.x * u4[q][0] + m.y * u4[q][1] + m.z * u4[q][2] + m.w * u4[q][3]; ss += m.x * m.x + m.y * m.y + m.z * m.z + m.w * m.w; }
;                 dd = wave_sum(dd); ss = wave_sum(ss);
.Lp2_procb_s5:
	v_mul_f32_e32 v132, v1, v159
	v_mul_f32_e32 v133, v1, v175
	v_mul_f32_e32 v134, v1, v191
	v_mul_f32_e32 v135, v1, v207
	v_mul_f32_e32 v152, v159, v159
	v_mul_f32_e32 v153, v175, v175
	v_mul_f32_e32 v222, v191, v191
	v_mul_f32_e32 v223, v207, v207
	v_fmac_f32_e32 v132, v0, v158
	v_fmac_f32_e32 v133, v0, v174
	v_fmac_f32_e32 v134, v0, v190
	v_fmac_f32_e32 v135, v0, v206
	v_fmac_f32_e32 v152, v158, v158
	v_fmac_f32_e32 v153, v174, v174
	v_fmac_f32_e32 v222, v190, v190
	v_fmac_f32_e32 v223, v206, v206
	v_fmac_f32_e32 v132, v2, v160
	v_fmac_f32_e32 v133, v2, v176
	v_fmac_f32_e32 v134, v2, v192
	v_fmac_f32_e32 v135, v2, v208
	v_fmac_f32_e32 v152, v160, v160
	v_fmac_f32_e32 v153, v176, v176
	v_fmac_f32_e32 v222, v192, v192
	v_fmac_f32_e32 v223, v208, v208
	v_fmac_f32_e32 v132, v3, v161
	v_fmac_f32_e32 v133, v3, v177
	v_fmac_f32_e32 v134, v3, v193
	v_fmac_f32_e32 v135, v3, v209
	v_fmac_f32_e32 v152, v161, v161
	v_fmac_f32_e32 v153, v177, v177
	v_fmac_f32_e32 v222, v193, v193
	v_fmac_f32_e32 v223, v209, v209
	v_add_f32_e32 v124, 0, v132
	v_add_f32_e32 v125, 0, v133
	v_add_f32_e32 v126, 0, v134
	v_add_f32_e32 v127, 0, v135
	v_mov_b32_e32 v128, v152
	v_mov_b32_e32 v129, v153
	v_mov_b32_e32 v130, v222
	v_mov_b32_e32 v131, v223
	v_mul_f32_e32 v132, v5, v163
	v_mul_f32_e32 v133, v5, v179
	v_mul_f32_e32 v134, v5, v195
	v_mul_f32_e32 v135, v5, v211
	v_mul_f32_e32 v152, v163, v163
	v_mul_f32_e32 v153, v179, v179
	v_mul_f32_e32 v222, v195, v195
	v_mul_f32_e32 v223, v211, v211
	v_fmac_f32_e32 v132, v4, v162
	v_fmac_f32_e32 v133, v4, v178
	v_fmac_f32_e32 v134, v4, v194
	v_fmac_f32_e32 v135, v4, v210
	v_fmac_f32_e32 v152, v162, v162
	v_fmac_f32_e32 v153, v178, v178
	v_fmac_f32_e32 v222, v194, v194
	v_fmac_f32_e32 v223, v210, v210
	v_fmac_f32_e32 v132, v6, v164
	v_fmac_f32_e32 v133, v6, v180
	v_fmac_f32_e32 v134, v6, v196
	v_fmac_f32_e32 v135, v6, v212
	v_fmac_f32_e32 v152, v164, v164
	v_fmac_f32_e32 v153, v180, v180
	v_fmac_f32_e32 v222, v196, v196
	v_fmac_f32_e32 v223, v212, v212
	v_fmac_f32_e32 v132, v7, v165
	v_fmac_f32_e32 v133, v7, v181
	v_fmac_f32_e32 v134, v7, v197
	v_fmac_f32_e32 v135, v7, v213
	v_fmac_f32_e32 v152, v165, v165
	v_fmac_f32_e32 v153, v181, v181
	v_fmac_f32_e32 v222, v197, v197
	v_fmac_f32_e32 v223, v213, v213
	v_add_f32_e32 v124, v124, v132
	v_add_f32_e32 v125, v125, v133
	v_add_f32_e32 v126, v126, v134
	v_add_f32_e32 v127, v127, v135
	v_add_f32_e32 v128, v128, v152
	v_add_f32_e32 v129, v129, v153
	v_add_f32_e32 v130, v130, v222
	v_add_f32_e32 v131, v131, v223
	v_mul_f32_e32 v132, v9, v167
	v_mul_f32_e32 v133, v9, v183
	v_mul_f32_e32 v134, v9, v199
	v_mul_f32_e32 v135, v9, v215
	v_mul_f32_e32 v152, v167, v167
	v_mul_f32_e32 v153, v183, v183
	v_mul_f32_e32 v222, v199, v199
	v_mul_f32_e32 v223, v215, v215
	v_fmac_f32_e32 v132, v8, v166
	v_fmac_f32_e32 v133, v8, v182
	v_fmac_f32_e32 v134, v8, v198
	v_fmac_f32_e32 v135, v8, v214
	v_fmac_f32_e32 v152, v166, v166
	v_fmac_f32_e32 v153, v182, v182
	v_fmac_f32_e32 v222, v198, v198
	v_fmac_f32_e32 v223, v214, v214
	v_fmac_f32_e32 v132, v10, v168
	v_fmac_f32_e32 v133, v10, v184
	v_fmac_f32_e32 v134, v10, v200
	v_fmac_f32_e32 v135, v10, v216
	v_fmac_f32_e32 v152, v168, v168
	v_fmac_f32_e32 v153, v184, v184
	v_fmac_f32_e32 v222, v200, v200
	v_fmac_f32_e32 v223, v216, v216
	v_fmac_f32_e32 v132, v11, v169
	v_fmac_f32_e32 v133, v11, v185
	v_fmac_f32_e32 v134, v11, v201
	v_fmac_f32_e32 v135, v11, v217
	v_fmac_f32_e32 v152, v169, v169
	v_fmac_f32_e32 v153, v185, v185
	v_fmac_f32_e32 v222, v201, v201
	v_fmac_f32_e32 v223, v217, v217
	v_add_f32_e32 v124, v124, v132
	v_add_f32_e32 v125, v125, v133
	v_add_f32_e32 v126, v126, v134
	v_add_f32_e32 v127, v127, v135
	v_add_f32_e32 v128, v128, v152
	v_add_f32_e32 v129, v129, v153
	v_add_f32_e32 v130, v130, v222
	v_add_f32_e32 v131, v131, v223
	v_mul_f32_e32 v132, v15, v171
	v_mul_f32_e32 v133, v15, v187
	v_mul_f32_e32 v134, v15, v203
	v_mul_f32_e32 v135, v15, v219
	v_mul_f32_e32 v152, v171, v171
	v_mul_f32_e32 v153, v187, v187
	v_mul_f32_e32 v222, v203, v203
	v_mul_f32_e32 v223, v219, v219
	v_fmac_f32_e32 v132, v14, v170
	v_fmac_f32_e32 v133, v14, v186
	v_fmac_f32_e32 v134, v14, v202
	v_fmac_f32_e32 v135, v14, v218
	v_fmac_f32_e32 v152, v170, v170
	v_fmac_f32_e32 v153, v186, v186
	v_fmac_f32_e32 v222, v202, v202
	v_fmac_f32_e32 v223, v218, v218
	v_fmac_f32_e32 v132, v16, v172
	v_fmac_f32_e32 v133, v16, v188
	v_fmac_f32_e32 v134, v16, v204
	v_fmac_f32_e32 v135, v16, v220
	v_fmac_f32_e32 v152, v172, v172
	v_fmac_f32_e32 v153, v188, v188
	v_fmac_f32_e32 v222, v204, v204
	v_fmac_f32_e32 v223, v220, v220
	v_fmac_f32_e32 v132, v17, v173
	v_fmac_f32_e32 v133, v17, v189
	v_fmac_f32_e32 v134, v17, v205
	v_fmac_f32_e32 v135, v17, v221
	v_fmac_f32_e32 v152, v173, v173
	v_fmac_f32_e32 v153, v189, v189
	v_fmac_f32_e32 v222, v205, v205
	v_fmac_f32_e32 v223, v221, v221
	v_add_f32_e32 v124, v124, v132
	v_add_f32_e32 v125, v125, v133
	v_add_f32_e32 v126, v126, v134
	v_add_f32_e32 v127, v127, v135
	v_add_f32_e32 v128, v128, v152
	v_add_f32_e32 v129, v129, v153
	v_add_f32_e32 v130, v130, v222
	v_add_f32_e32 v131, v131, v223
	ds_bpermute_b32 v132, v95, v124
	ds_bpermute_b32 v133, v95, v125
	ds_bpermute_b32 v134, v95, v126
	ds_bpermute_b32 v135, v95, v127
	ds_bpermute_b32 v152, v95, v128
	ds_bpermute_b32 v153, v95, v129
	ds_bpermute_b32 v222, v95, v130
	ds_bpermute_b32 v223, v95, v131
	s_waitcnt lgkmcnt(7)
	v_add_f32_e32 v124, v124, v132
	s_waitcnt lgkmcnt(6)
	v_add_f32_e32 v125, v125, v133
	s_waitcnt lgkmcnt(5)
	v_add_f32_e32 v126, v126, v134
	s_waitcnt lgkmcnt(4)
	v_add_f32_e32 v127, v127, v135
	s_waitcnt lgkmcnt(3)
; DI float wave_sum(float v) {
; #pragma unroll
;     for (int o = 32; o; o >>= 1) v += __shfl_xor(v, o);
;     return v;
; DI void tok0_mem(ldsp lds, const float* qm, const float* memb, const float* mnw, const float* Wkv, int hm, LAS float* out64, int tid, int wid, int lane) {
;     ...
;             for (int r = 0; r < 4; ++r) {
;                 const int n = wid * 32 + i0 + r; float dd = 0.f, ss = 0.f;
; #pragma unroll
;                 for (int q = 0; q < 4; ++q) { const float4 m = m4[r][q];
;                     dd += m.x * u4[q][0] + m.y * u4[q][1] + m.z * u4[q][2] + m.w * u4[q][3]; ss += m.x * m.x + m.y * m.y + m.z * m.z + m.w * m.w; }
;                 dd = wave_sum(dd); ss = wave_sum(ss);
;                 if (lane == 0) { const float rstd = rsqrtf(ss * (1.0f / 1024.0f) + 1e-6f); SC[n] = dd * rstd * 0.125f; RSN[n] = rstd; }
;             }
	v_add_f32_e32 v128, v128, v152
	s_waitcnt lgkmcnt(2)
	v_add_f32_e32 v129, v129, v153
	s_waitcnt lgkmcnt(1)
	v_add_f32_e32 v130, v130, v222
	s_waitcnt lgkmcnt(0)
	v_add_f32_e32 v131, v131, v223
	ds_bpermute_b32 v132, v96, v124
	ds_bpermute_b32 v133, v96, v125
	ds_bpermute_b32 v134, v96, v126
	ds_bpermute_b32 v135, v96, v127
	ds_bpermute_b32 v152, v96, v128
	ds_bpermute_b32 v153, v96, v129
	ds_bpermute_b32 v222, v96, v130
	ds_bpermute_b32 v223, v96, v131
	s_waitcnt lgkmcnt(7)
	v_add_f32_e32 v124, v124, v132
	s_waitcnt lgkmcnt(6)
	v_add_f32_e32 v125, v125, v133
	s_waitcnt lgkmcnt(5)
	v_add_f32_e32 v126, v126, v134
	s_waitcnt lgkmcnt(4)
	v_add_f32_e32 v127, v127, v135
	s_waitcnt lgkmcnt(3)
	v_add_f32_e32 v128, v128, v152
	s_waitcnt lgkmcnt(2)
	v_add_f32_e32 v129, v129, v153
	s_waitcnt lgkmcnt(1)
	v_add_f32_e32 v130, v130, v222
	s_waitcnt lgkmcnt(0)
	v_add_f32_e32 v131, v131, v223
	ds_bpermute_b32 v132, v97, v124
	ds_bpermute_b32 v133, v97, v125
	ds_bpermute_b32 v134, v97, v126
	ds_bpermute_b32 v135, v97, v127
	ds_bpermute_b32 v152, v97, v128
	ds_bpermute_b32 v153, v97, v129
	ds_bpermute_b32 v222, v97, v130
	ds_bpermute_b32 v223, v97, v131
	s_waitcnt lgkmcnt(7)
	v_add_f32_e32 v124, v124, v132
	s_waitcnt lgkmcnt(6)
	v_add_f32_e32 v125, v125, v133
	s_waitcnt lgkmcnt(5)
	v_add_f32_e32 v126, v126, v134
	s_waitcnt lgkmcnt(4)
	v_add_f32_e32 v127, v127, v135
	s_waitcnt lgkmcnt(3)
	v_add_f32_e32 v128, v128, v152
	s_waitcnt lgkmcnt(2)
	v_add_f32_e32 v129, v129, v153
	s_waitcnt lgkmcnt(1)
	v_add_f32_e32 v130, v130, v222
	s_waitcnt lgkmcnt(0)
	v_add_f32_e32 v131, v131, v223
	ds_bpermute_b32 v132, v98, v124
	ds_bpermute_b32 v133, v98, v125
	ds_bpermute_b32 v134, v98, v126
	ds_bpermute_b32 v135, v98, v127
	ds_bpermute_b32 v152, v98, v128
	ds_bpermute_b32 v153, v98, v129
	ds_bpermute_b32 v222, v98, v130
	ds_bpermute_b32 v223, v98, v131
	s_waitcnt lgkmcnt(7)
	v_add_f32_e32 v124, v124, v132
	s_waitcnt lgkmcnt(6)
	v_add_f32_e32 v125, v125, v133
	s_waitcnt lgkmcnt(5)
	v_add_f32_e32 v126, v126, v134
	s_waitcnt lgkmcnt(4)
	v_add_f32_e32 v127, v127, v135
	s_waitcnt lgkmcnt(3)
	v_add_f32_e32 v128, v128, v152
	s_waitcnt lgkmcnt(2)
	v_add_f32_e32 v129, v129, v153
	s_waitcnt lgkmcnt(1)
	v_add_f32_e32 v130, v130, v222
	s_waitcnt lgkmcnt(0)
	v_add_f32_e32 v131, v131, v223
	ds_bpermute_b32 v132, v99, v124
	ds_bpermute_b32 v133, v99, v125
	ds_bpermute_b32 v134, v99, v126
	ds_bpermute_b32 v135, v99, v127
	ds_bpermute_b32 v152, v99, v128
	ds_bpermute_b32 v153, v99, v129
	ds_bpermute_b32 v222, v99, v130
	ds_bpermute_b32 v223, v99, v131
	s_waitcnt lgkmcnt(7)
	v_add_f32_e32 v124, v124, v132
	s_waitcnt lgkmcnt(6)
	v_add_f32_e32 v125, v125, v133
	s_waitcnt lgkmcnt(5)
	v_add_f32_e32 v126, v126, v134
	s_waitcnt lgkmcnt(4)
	v_add_f32_e32 v127, v127, v135
	s_waitcnt lgkmcnt(3)
	v_add_f32_e32 v128, v128, v152
	s_waitcnt lgkmcnt(2)
	v_add_f32_e32 v129, v129, v153
	s_waitcnt lgkmcnt(1)
	v_add_f32_e32 v130, v130, v222
	s_waitcnt lgkmcnt(0)
	v_add_f32_e32 v131, v131, v223
	ds_bpermute_b32 v132, v100, v124
	ds_bpermute_b32 v133, v100, v125
	ds_bpermute_b32 v134, v100, v126
	ds_bpermute_b32 v135, v100, v127
	ds_bpermute_b32 v152, v100, v128
	ds_bpermute_b32 v153, v100, v129
	ds_bpermute_b32 v222, v100, v130
	ds_bpermute_b32 v223, v100, v131
	s_waitcnt lgkmcnt(7)
	v_add_f32_e32 v124, v124, v132
	s_waitcnt lgkmcnt(6)
	v_add_f32_e32 v125, v125, v133
	s_waitcnt lgkmcnt(5)
	v_add_f32_e32 v126, v126, v134
	s_waitcnt lgkmcnt(4)
	v_add_f32_e32 v127, v127, v135
	s_waitcnt lgkmcnt(3)
	v_add_f32_e32 v128, v128, v152
	s_waitcnt lgkmcnt(2)
	v_add_f32_e32 v129, v129, v153
	s_waitcnt lgkmcnt(1)
	v_add_f32_e32 v130, v130, v222
	s_waitcnt lgkmcnt(0)
	v_add_f32_e32 v131, v131, v223
	s_and_saveexec_b64 s[22:23], s[40:41]
	v_fmamk_f32 v128, v128, 0x3a800000, v231
	v_mul_f32_e32 v132, 0x4b800000, v128
	v_cmp_gt_f32_e32 vcc, s33, v128
	s_nop 1
	v_cndmask_b32_e32 v128, v128, v132, vcc
	v_rsq_f32_e32 v128, v128
	s_nop 0
	v_mul_f32_e32 v132, 0x45800000, v128
	v_cndmask_b32_e32 v132, v128, v132, vcc
	v_mul_f32_e32 v124, v124, v132
	v_mul_f32_e32 v124, 0x3e000000, v124
	v_add_u32_e64 v152, 16, s30
	ds_write2st64_b32 v152, v124, v132 offset1:4
	v_fmamk_f32 v129, v129, 0x3a800000, v231
	v_mul_f32_e32 v133, 0x4b800000, v129
	v_cmp_gt_f32_e32 vcc, s33, v129
	s_nop 1
	v_cndmask_b32_e32 v129, v129, v133, vcc
	v_rsq_f32_e32 v129, v129
	s_nop 0
	v_mul_f32_e32 v133, 0x45800000, v129
	v_cndmask_b32_e32 v133, v129, v133, vcc
	v_mul_f32_e32 v125, v125, v133
	v_mul_f32_e32 v125, 0x3e000000, v125
	v_add_u32_e64 v153, 20, s30
	ds_write2st64_b32 v153, v125, v133 offset1:4
	v_fmamk_f32 v130, v130, 0x3a800000, v231
	v_mul_f32_e32 v134, 0x4b800000, v130
	v_cmp_gt_f32_e32 vcc, s33, v130
	s_nop 1
	v_cndmask_b32_e32 v130, v130, v134, vcc
	v_rsq_f32_e32 v130, v130
	s_nop 0
	v_mul_f32_e32 v134, 0x45800000, v130
	v_cndmask_b32_e32 v134, v130, v134, vcc
	v_mul_f32_e32 v126, v126, v134
	v_mul_f32_e32 v126, 0x3e000000, v126
	v_add_u32_e64 v222, 24, s30
	ds_write2st64_b32 v222, v126, v134 offset1:4
	v_fmamk_f32 v131, v131, 0x3a800000, v231
	v_mul_f32_e32 v135, 0x4b800000, v131
	v_cmp_gt_f32_e32 vcc, s33, v131
	s_nop 1
	v_cndmask_b32_e32 v131, v131, v135, vcc
	v_rsq_f32_e32 v131, v131
	s_nop 0
	v_mul_f32_e32 v135, 0x45800000, v131
	v_cndmask_b32_e32 v135, v131, v135, vcc
	v_mul_f32_e32 v127, v127, v135
	v_mul_f32_e32 v127, 0x3e000000, v127
	v_add_u32_e64 v223, 28, s30
	ds_write2st64_b32 v223, v127, v135 offset1:4
	s_or_b64 exec, exec, s[22:23]
	s_add_i32 s0, s0, 8
	s_add_i32 s30, s30, 32
	s_cmp_gt_u32 s0, 27
	s_cbranch_scc0 .LBB0_100
	s_branch .LBB0_108

; DI void tok0_mem(ldsp lds, const float* qm, const float* memb, const float* mnw, const float* Wkv, int hm, LAS float* out64, int tid, int wid, int lane) {
;     ...
;         for (int i0 = 0; i0 < 32; i0 += 4) {
;             float4 m4[4][4];
; #pragma unroll
;             for (int r = 0; r < 4; ++r) { const float* mr = memb + (size_t)(wid * 32 + i0 + r) * 1024;
; #pragma unroll
;                 for (int q = 0; q < 4; ++q) m4[r][q] = *(const float4*)(mr + q * 256 + lane * 4); }
; #pragma unroll
;             for (int r = 0; r < 4; ++r) {
;                 const int n = wid * 32 + i0 + r; float dd = 0.f, ss = 0.f;
; #pragma unroll
;                 for (int q = 0; q < 4; ++q) { const float4 m = m4[r][q];
;                     dd += m.x * u4[q][0] + m.y * u4[q][1] + m.z * u4[q][2] + m.w * u4[q][3]; ss += m.x * m.x + m.y * m.y + m.z * m.z + m.w * m.w; }
.Lp2_entry_s2:
	s_movk_i32 s22, 0xf000
	v_add_co_u32_e32 v248, vcc, 0xffffd000, v94
	s_nop 1
	v_addc_co_u32_e32 v249, vcc, -1, v95, vcc
	global_load_dwordx4 v[112:115], v[248:249], off offset:-3084
	global_load_dwordx4 v[116:119], v[248:249], off offset:-2060
	global_load_dwordx4 v[74:77], v[248:249], off offset:-1036
	global_load_dwordx4 v[70:73], v[248:249], off offset:-12
	v_add_co_u32_e32 v248, vcc, s21, v94
	s_nop 1
	v_addc_co_u32_e32 v249, vcc, -1, v95, vcc
	global_load_dwordx4 v[66:69], v[248:249], off offset:-3084
	global_load_dwordx4 v[62:65], v[248:249], off offset:-2060
	global_load_dwordx4 v[58:61], v[248:249], off offset:-1036
	global_load_dwordx4 v[54:57], v[248:249], off offset:-12
	v_add_co_u32_e32 v248, vcc, s22, v94
	s_nop 1
	v_addc_co_u32_e32 v249, vcc, -1, v95, vcc
	global_load_dwordx4 v[50:53], v[248:249], off offset:-3084
	global_load_dwordx4 v[46:49], v[248:249], off offset:-2060
	global_load_dwordx4 v[42:45], v[248:249], off offset:-1036
	global_load_dwordx4 v[38:41], v[248:249], off offset:-12
	global_load_dwordx4 v[34:37], v[94:95], off offset:-3084
	global_load_dwordx4 v[26:29], v[94:95], off offset:-2060
	global_load_dwordx4 v[22:25], v[94:95], off offset:-1036
	global_load_dwordx4 v[18:21], v[94:95], off offset:-12
.LBB0_834:
	v_lshl_add_u64 v[246:247], v[94:95], 0, s[24:25]
	s_movk_i32 s22, 0xf000
	v_add_co_u32_e32 v248, vcc, 0xffffd000, v246
	s_nop 1
	v_addc_co_u32_e32 v249, vcc, -1, v247, vcc
	global_load_dwordx4 v[158:161], v[248:249], off offset:-3084
	global_load_dwordx4 v[162:165], v[248:249], off offset:-2060
	global_load_dwordx4 v[166:169], v[248:249], off offset:-1036
	global_load_dwordx4 v[170:173], v[248:249], off offset:-12
	v_add_co_u32_e32 v248, vcc, s21, v246
	s_nop 1
	v_addc_co_u32_e32 v249, vcc, -1, v247, vcc
	global_load_dwordx4 v[174:177], v[248:249], off offset:-3084
	global_load_dwordx4 v[178:181], v[248:249], off offset:-2060
	global_load_dwordx4 v[182:185], v[248:249], off offset:-1036
	global_load_dwordx4 v[186:189], v[248:249], off offset:-12
	v_add_co_u32_e32 v248, vcc, s22, v246
	s_nop 1
	v_addc_co_u32_e32 v249, vcc, -1, v247, vcc
	global_load_dwordx4 v[190:193], v[248:249], off offset:-3084
	global_load_dwordx4 v[194:197], v[248:249], off offset:-2060
	global_load_dwordx4 v[198:201], v[248:249], off offset:-1036
	global_load_dwordx4 v[202:205], v[248:249], off offset:-12
	global_load_dwordx4 v[206:209], v[246:247], off offset:-3084
	global_load_dwordx4 v[210:213], v[246:247], off offset:-2060
	global_load_dwordx4 v[214:217], v[246:247], off offset:-1036
	global_load_dwordx4 v[218:221], v[246:247], off offset:-12
	s_waitcnt vmcnt(16) lgkmcnt(0)
	v_mul_f32_e32 v132, v1, v113
	v_mul_f32_e32 v133, v1, v67
	v_mul_f32_e32 v134, v1, v51
	v_mul_f32_e32 v135, v1, v35
	v_mul_f32_e32 v152, v113, v113
	v_mul_f32_e32 v153, v67, v67
	v_mul_f32_e32 v222, v51, v51
	v_mul_f32_e32 v223, v35, v35
	v_fmac_f32_e32 v132, v0, v112
	v_fmac_f32_e32 v133, v0, v66
	v_fmac_f32_e32 v134, v0, v50
	v_fmac_f32_e32 v135, v0, v34
	v_fmac_f32_e32 v152, v112, v112
	v_fmac_f32_e32 v153, v66, v66
	v_fmac_f32_e32 v222, v50, v50
	v_fmac_f32_e32 v223, v34, v34
	v_fmac_f32_e32 v132, v2, v114
	v_fmac_f32_e32 v133, v2, v68
	v_fmac_f32_e32 v134, v2, v52
	v_fmac_f32_e32 v135, v2, v36
	v_fmac_f32_e32 v152, v114, v114
	v_fmac_f32_e32 v153, v68, v68
	v_fmac_f32_e32 v222, v52, v52
	v_fmac_f32_e32 v223, v36, v36
	v_fmac_f32_e32 v132, v3, v115
	v_fmac_f32_e32 v133, v3, v69
	v_fmac_f32_e32 v134, v3, v53
	v_fmac_f32_e32 v135, v3, v37
	v_fmac_f32_e32 v152, v115, v115
	v_fmac_f32_e32 v153, v69, v69
	v_fmac_f32_e32 v222, v53, v53
	v_fmac_f32_e32 v223, v37, v37
	v_add_f32_e32 v124, 0, v132
	v_add_f32_e32 v125, 0, v133
	v_add_f32_e32 v126, 0, v134
	v_add_f32_e32 v127, 0, v135
	v_mov_b32_e32 v128, v152
	v_mov_b32_e32 v129, v153
	v_mov_b32_e32 v130, v222
	v_mov_b32_e32 v131, v223
	v_mul_f32_e32 v132, v5, v117
	v_mul_f32_e32 v133, v5, v63
	v_mul_f32_e32 v134, v5, v47
	v_mul_f32_e32 v135, v5, v27
	v_mul_f32_e32 v152, v117, v117
	v_mul_f32_e32 v153, v63, v63
	v_mul_f32_e32 v222, v47, v47
	v_mul_f32_e32 v223, v27, v27
	v_fmac_f32_e32 v132, v4, v116
	v_fmac_f32_e32 v133, v4, v62
	v_fmac_f32_e32 v134, v4, v46
	v_fmac_f32_e32 v135, v4, v26
	v_fmac_f32_e32 v152, v116, v116
	v_fmac_f32_e32 v153, v62, v62
	v_fmac_f32_e32 v222, v46, v46
	v_fmac_f32_e32 v223, v26, v26
	v_fmac_f32_e32 v132, v6, v118
	v_fmac_f32_e32 v133, v6, v64
	v_fmac_f32_e32 v134, v6, v48
	v_fmac_f32_e32 v135, v6, v28
	v_fmac_f32_e32 v152, v118, v118
	v_fmac_f32_e32 v153, v64, v64
	v_fmac_f32_e32 v222, v48, v48
	v_fmac_f32_e32 v223, v28, v28
	v_fmac_f32_e32 v132, v7, v119
	v_fmac_f32_e32 v133, v7, v65
	v_fmac_f32_e32 v134, v7, v49
	v_fmac_f32_e32 v135, v7, v29
	v_fmac_f32_e32 v152, v119, v119
	v_fmac_f32_e32 v153, v65, v65
	v_fmac_f32_e32 v222, v49, v49
	v_fmac_f32_e32 v223, v29, v29
	v_add_f32_e32 v124, v124, v132
	v_add_f32_e32 v125, v125, v133
	v_add_f32_e32 v126, v126, v134
	v_add_f32_e32 v127, v127, v135
	v_add_f32_e32 v128, v128, v152
	v_add_f32_e32 v129, v129, v153
	v_add_f32_e32 v130, v130, v222
	v_add_f32_e32 v131, v131, v223
	v_mul_f32_e32 v132, v9, v75
	v_mul_f32_e32 v133, v9, v59
	v_mul_f32_e32 v134, v9, v43
	v_mul_f32_e32 v135, v9, v23
	v_mul_f32_e32 v152, v75, v75
	v_mul_f32_e32 v153, v59, v59
	v_mul_f32_e32 v222, v43, v43
	v_mul_f32_e32 v223, v23, v23
	v_fmac_f32_e32 v132, v8, v74
	v_fmac_f32_e32 v133, v8, v58
	v_fmac_f32_e32 v134, v8, v42
	v_fmac_f32_e32 v135, v8, v22
	v_fmac_f32_e32 v152, v74, v74
	v_fmac_f32_e32 v153, v58, v58
	v_fmac_f32_e32 v222, v42, v42
	v_fmac_f32_e32 v223, v22, v22
	v_fmac_f32_e32 v132, v10, v76
	v_fmac_f32_e32 v133, v10, v60
; DI float wave_sum(float v) {
; #pragma unroll
;     for (int o = 32; o; o >>= 1) v += __shfl_xor(v, o);
;     return v;
; DI void tok0_mem(ldsp lds, const float* qm, const float* memb, const float* mnw, const float* Wkv, int hm, LAS float* out64, int tid, int wid, int lane) {
;     ...
; #pragma unroll
;                 for (int q = 0; q < 4; ++q) { const float4 m = m4[r][q];
;                     dd += m.x * u4[q][0] + m.y * u4[q][1] + m.z * u4[q][2] + m.w * u4[q][3]; ss += m.x * m.x + m.y * m.y + m.z * m.z + m.w * m.w; }
;                 dd = wave_sum(dd); ss = wave_sum(ss);
	v_fmac_f32_e32 v134, v10, v44
	v_fmac_f32_e32 v135, v10, v24
	v_fmac_f32_e32 v152, v76, v76
	v_fmac_f32_e32 v153, v60, v60
	v_fmac_f32_e32 v222, v44, v44
	v_fmac_f32_e32 v223, v24, v24
	v_fmac_f32_e32 v132, v11, v77
	v_fmac_f32_e32 v133, v11, v61
	v_fmac_f32_e32 v134, v11, v45
	v_fmac_f32_e32 v135, v11, v25
	v_fmac_f32_e32 v152, v77, v77
	v_fmac_f32_e32 v153, v61, v61
	v_fmac_f32_e32 v222, v45, v45
	v_fmac_f32_e32 v223, v25, v25
	v_add_f32_e32 v124, v124, v132
	v_add_f32_e32 v125, v125, v133
	v_add_f32_e32 v126, v126, v134
	v_add_f32_e32 v127, v127, v135
	v_add_f32_e32 v128, v128, v152
	v_add_f32_e32 v129, v129, v153
	v_add_f32_e32 v130, v130, v222
	v_add_f32_e32 v131, v131, v223
	v_mul_f32_e32 v132, v15, v71
	v_mul_f32_e32 v133, v15, v55
	v_mul_f32_e32 v134, v15, v39
	v_mul_f32_e32 v135, v15, v19
	v_mul_f32_e32 v152, v71, v71
	v_mul_f32_e32 v153, v55, v55
	v_mul_f32_e32 v222, v39, v39
	v_mul_f32_e32 v223, v19, v19
	v_fmac_f32_e32 v132, v14, v70
	v_fmac_f32_e32 v133, v14, v54
	v_fmac_f32_e32 v134, v14, v38
	v_fmac_f32_e32 v135, v14, v18
	v_fmac_f32_e32 v152, v70, v70
	v_fmac_f32_e32 v153, v54, v54
	v_fmac_f32_e32 v222, v38, v38
	v_fmac_f32_e32 v223, v18, v18
	v_fmac_f32_e32 v132, v16, v72
	v_fmac_f32_e32 v133, v16, v56
	v_fmac_f32_e32 v134, v16, v40
	v_fmac_f32_e32 v135, v16, v20
	v_fmac_f32_e32 v152, v72, v72
	v_fmac_f32_e32 v153, v56, v56
	v_fmac_f32_e32 v222, v40, v40
	v_fmac_f32_e32 v223, v20, v20
	v_fmac_f32_e32 v132, v17, v73
	v_fmac_f32_e32 v133, v17, v57
	v_fmac_f32_e32 v134, v17, v41
	v_fmac_f32_e32 v135, v17, v21
	v_fmac_f32_e32 v152, v73, v73
	v_fmac_f32_e32 v153, v57, v57
	v_fmac_f32_e32 v222, v41, v41
	v_fmac_f32_e32 v223, v21, v21
	v_add_f32_e32 v124, v124, v132
	v_add_f32_e32 v125, v125, v133
	v_add_f32_e32 v126, v126, v134
	v_add_f32_e32 v127, v127, v135
	v_add_f32_e32 v128, v128, v152
	v_add_f32_e32 v129, v129, v153
	v_add_f32_e32 v130, v130, v222
	v_add_f32_e32 v131, v131, v223
	ds_bpermute_b32 v132, v97, v124
	ds_bpermute_b32 v133, v97, v125
	ds_bpermute_b32 v134, v97, v126
	ds_bpermute_b32 v135, v97, v127
	ds_bpermute_b32 v152, v97, v128
	ds_bpermute_b32 v153, v97, v129
	ds_bpermute_b32 v222, v97, v130
	ds_bpermute_b32 v223, v97, v131
	s_waitcnt lgkmcnt(7)
	v_add_f32_e32 v124, v124, v132
	s_waitcnt lgkmcnt(6)
	v_add_f32_e32 v125, v125, v133
	s_waitcnt lgkmcnt(5)
	v_add_f32_e32 v126, v126, v134
	s_waitcnt lgkmcnt(4)
	v_add_f32_e32 v127, v127, v135
	s_waitcnt lgkmcnt(3)
	v_add_f32_e32 v128, v128, v152
	s_waitcnt lgkmcnt(2)
	v_add_f32_e32 v129, v129, v153
	s_waitcnt lgkmcnt(1)
	v_add_f32_e32 v130, v130, v222
	s_waitcnt lgkmcnt(0)
	v_add_f32_e32 v131, v131, v223
	ds_bpermute_b32 v132, v98, v124
	ds_bpermute_b32 v133, v98, v125
	ds_bpermute_b32 v134, v98, v126
	ds_bpermute_b32 v135, v98, v127
	ds_bpermute_b32 v152, v98, v128
	ds_bpermute_b32 v153, v98, v129
	ds_bpermute_b32 v222, v98, v130
	ds_bpermute_b32 v223, v98, v131
	s_waitcnt lgkmcnt(7)
	v_add_f32_e32 v124, v124, v132
	s_waitcnt lgkmcnt(6)
	v_add_f32_e32 v125, v125, v133
	s_waitcnt lgkmcnt(5)
	v_add_f32_e32 v126, v126, v134
	s_waitcnt lgkmcnt(4)
	v_add_f32_e32 v127, v127, v135
	s_waitcnt lgkmcnt(3)
	v_add_f32_e32 v128, v128, v152
	s_waitcnt lgkmcnt(2)
	v_add_f32_e32 v129, v129, v153
	s_waitcnt lgkmcnt(1)
	v_add_f32_e32 v130, v130, v222
	s_waitcnt lgkmcnt(0)
	v_add_f32_e32 v131, v131, v223
	ds_bpermute_b32 v132, v99, v124
	ds_bpermute_b32 v133, v99, v125
	ds_bpermute_b32 v134, v99, v126
	ds_bpermute_b32 v135, v99, v127
	ds_bpermute_b32 v152, v99, v128
	ds_bpermute_b32 v153, v99, v129
	ds_bpermute_b32 v222, v99, v130
	ds_bpermute_b32 v223, v99, v131
	s_waitcnt lgkmcnt(7)
	v_add_f32_e32 v124, v124, v132
	s_waitcnt lgkmcnt(6)
	v_add_f32_e32 v125, v125, v133
	s_waitcnt lgkmcnt(5)
	v_add_f32_e32 v126, v126, v134
	s_waitcnt lgkmcnt(4)
	v_add_f32_e32 v127, v127, v135
	s_waitcnt lgkmcnt(3)
	v_add_f32_e32 v128, v128, v152
	s_waitcnt lgkmcnt(2)
	v_add_f32_e32 v129, v129, v153
	s_waitcnt lgkmcnt(1)
	v_add_f32_e32 v130, v130, v222
	s_waitcnt lgkmcnt(0)
	v_add_f32_e32 v131, v131, v223
	ds_bpermute_b32 v132, v100, v124
	ds_bpermute_b32 v133, v100, v125
	ds_bpermute_b32 v134, v100, v126
	ds_bpermute_b32 v135, v100, v127
	ds_bpermute_b32 v152, v100, v128
	ds_bpermute_b32 v153, v100, v129
	ds_bpermute_b32 v222, v100, v130
	ds_bpermute_b32 v223, v100, v131
	s_waitcnt lgkmcnt(7)
	v_add_f32_e32 v124, v124, v132
	s_waitcnt lgkmcnt(6)
	v_add_f32_e32 v125, v125, v133
	s_waitcnt lgkmcnt(5)
	v_add_f32_e32 v126, v126, v134
	s_waitcnt lgkmcnt(4)
	v_add_f32_e32 v127, v127, v135
	s_waitcnt lgkmcnt(3)
	v_add_f32_e32 v128, v128, v152
	s_waitcnt lgkmcnt(2)
	v_add_f32_e32 v129, v129, v153
	s_waitcnt lgkmcnt(1)
; DI void tok0_mem(ldsp lds, const float* qm, const float* memb, const float* mnw, const float* Wkv, int hm, LAS float* out64, int tid, int wid, int lane) {
;     ...
;         for (int i0 = 0; i0 < 32; i0 += 4) {
;             float4 m4[4][4];
; #pragma unroll
;             for (int r = 0; r < 4; ++r) { const float* mr = memb + (size_t)(wid * 32 + i0 + r) * 1024;
; #pragma unroll
;                 for (int q = 0; q < 4; ++q) m4[r][q] = *(const float4*)(mr + q * 256 + lane * 4); }
;     ...
;                 dd = wave_sum(dd); ss = wave_sum(ss);
;                 if (lane == 0) { const float rstd = rsqrtf(ss * (1.0f / 1024.0f) + 1e-6f); SC[n] = dd * rstd * 0.125f; RSN[n] = rstd; }
;             }
	v_add_f32_e32 v130, v130, v222
	s_waitcnt lgkmcnt(0)
	v_add_f32_e32 v131, v131, v223
	ds_bpermute_b32 v132, v101, v124
	ds_bpermute_b32 v133, v101, v125
	ds_bpermute_b32 v134, v101, v126
	ds_bpermute_b32 v135, v101, v127
	ds_bpermute_b32 v152, v101, v128
	ds_bpermute_b32 v153, v101, v129
	ds_bpermute_b32 v222, v101, v130
	ds_bpermute_b32 v223, v101, v131
	s_waitcnt lgkmcnt(7)
	v_add_f32_e32 v124, v124, v132
	s_waitcnt lgkmcnt(6)
	v_add_f32_e32 v125, v125, v133
	s_waitcnt lgkmcnt(5)
	v_add_f32_e32 v126, v126, v134
	s_waitcnt lgkmcnt(4)
	v_add_f32_e32 v127, v127, v135
	s_waitcnt lgkmcnt(3)
	v_add_f32_e32 v128, v128, v152
	s_waitcnt lgkmcnt(2)
	v_add_f32_e32 v129, v129, v153
	s_waitcnt lgkmcnt(1)
	v_add_f32_e32 v130, v130, v222
	s_waitcnt lgkmcnt(0)
	v_add_f32_e32 v131, v131, v223
	ds_bpermute_b32 v132, v102, v124
	ds_bpermute_b32 v133, v102, v125
	ds_bpermute_b32 v134, v102, v126
	ds_bpermute_b32 v135, v102, v127
	ds_bpermute_b32 v152, v102, v128
	ds_bpermute_b32 v153, v102, v129
	ds_bpermute_b32 v222, v102, v130
	ds_bpermute_b32 v223, v102, v131
	s_waitcnt lgkmcnt(7)
	v_add_f32_e32 v124, v124, v132
	s_waitcnt lgkmcnt(6)
	v_add_f32_e32 v125, v125, v133
	s_waitcnt lgkmcnt(5)
	v_add_f32_e32 v126, v126, v134
	s_waitcnt lgkmcnt(4)
	v_add_f32_e32 v127, v127, v135
	s_waitcnt lgkmcnt(3)
	v_add_f32_e32 v128, v128, v152
	s_waitcnt lgkmcnt(2)
	v_add_f32_e32 v129, v129, v153
	s_waitcnt lgkmcnt(1)
	v_add_f32_e32 v130, v130, v222
	s_waitcnt lgkmcnt(0)
	v_add_f32_e32 v131, v131, v223
	s_and_saveexec_b64 s[22:23], s[40:41]
	v_fmamk_f32 v128, v128, 0x3a800000, v231
	v_mul_f32_e32 v132, 0x4b800000, v128
	v_cmp_gt_f32_e32 vcc, s33, v128
	s_nop 1
	v_cndmask_b32_e32 v128, v128, v132, vcc
	v_rsq_f32_e32 v128, v128
	s_nop 0
	v_mul_f32_e32 v132, 0x45800000, v128
	v_cndmask_b32_e32 v132, v128, v132, vcc
	v_mul_f32_e32 v124, v124, v132
	v_mul_f32_e32 v124, 0x3e000000, v124
	v_mov_b32_e32 v152, s30
	ds_write2st64_b32 v152, v124, v132 offset1:4
	v_fmamk_f32 v129, v129, 0x3a800000, v231
	v_mul_f32_e32 v133, 0x4b800000, v129
	v_cmp_gt_f32_e32 vcc, s33, v129
	s_nop 1
	v_cndmask_b32_e32 v129, v129, v133, vcc
	v_rsq_f32_e32 v129, v129
	s_nop 0
	v_mul_f32_e32 v133, 0x45800000, v129
	v_cndmask_b32_e32 v133, v129, v133, vcc
	v_mul_f32_e32 v125, v125, v133
	v_mul_f32_e32 v125, 0x3e000000, v125
	v_add_u32_e64 v153, 4, s30
	ds_write2st64_b32 v153, v125, v133 offset1:4
	v_fmamk_f32 v130, v130, 0x3a800000, v231
	v_mul_f32_e32 v134, 0x4b800000, v130
	v_cmp_gt_f32_e32 vcc, s33, v130
	s_nop 1
	v_cndmask_b32_e32 v130, v130, v134, vcc
	v_rsq_f32_e32 v130, v130
	s_nop 0
	v_mul_f32_e32 v134, 0x45800000, v130
	v_cndmask_b32_e32 v134, v130, v134, vcc
	v_mul_f32_e32 v126, v126, v134
	v_mul_f32_e32 v126, 0x3e000000, v126
	v_add_u32_e64 v222, 8, s30
	ds_write2st64_b32 v222, v126, v134 offset1:4
	v_fmamk_f32 v131, v131, 0x3a800000, v231
	v_mul_f32_e32 v135, 0x4b800000, v131
	v_cmp_gt_f32_e32 vcc, s33, v131
	s_nop 1
	v_cndmask_b32_e32 v131, v131, v135, vcc
	v_rsq_f32_e32 v131, v131
	s_nop 0
	v_mul_f32_e32 v135, 0x45800000, v131
	v_cndmask_b32_e32 v135, v131, v135, vcc
	v_mul_f32_e32 v127, v127, v135
	v_mul_f32_e32 v127, 0x3e000000, v127
	v_add_u32_e64 v223, 12, s30
	ds_write2st64_b32 v223, v127, v135 offset1:4
	s_or_b64 exec, exec, s[22:23]
	v_lshl_add_u64 v[94:95], v[246:247], 0, s[24:25]
	s_cmp_gt_i32 s0, 19
	s_cbranch_scc1 .Lp2_last_s2
	s_movk_i32 s22, 0xf000
	v_add_co_u32_e32 v248, vcc, 0xffffd000, v94
	s_nop 1
	v_addc_co_u32_e32 v249, vcc, -1, v95, vcc
	global_load_dwordx4 v[112:115], v[248:249], off offset:-3084
	global_load_dwordx4 v[116:119], v[248:249], off offset:-2060
	global_load_dwordx4 v[74:77], v[248:249], off offset:-1036
	global_load_dwordx4 v[70:73], v[248:249], off offset:-12
	v_add_co_u32_e32 v248, vcc, s21, v94
	s_nop 1
	v_addc_co_u32_e32 v249, vcc, -1, v95, vcc
	global_load_dwordx4 v[66:69], v[248:249], off offset:-3084
	global_load_dwordx4 v[62:65], v[248:249], off offset:-2060
	global_load_dwordx4 v[58:61], v[248:249], off offset:-1036
	global_load_dwordx4 v[54:57], v[248:249], off offset:-12
	v_add_co_u32_e32 v248, vcc, s22, v94
	s_nop 1
	v_addc_co_u32_e32 v249, vcc, -1, v95, vcc
	global_load_dwordx4 v[50:53], v[248:249], off offset:-3084
	global_load_dwordx4 v[46:49], v[248:249], off offset:-2060
	global_load_dwordx4 v[42:45], v[248:249], off offset:-1036
	global_load_dwordx4 v[38:41], v[248:249], off offset:-12
	global_load_dwordx4 v[34:37], v[94:95], off offset:-3084
	global_load_dwordx4 v[26:29], v[94:95], off offset:-2060
	global_load_dwordx4 v[22:25], v[94:95], off offset:-1036
	global_load_dwordx4 v[18:21], v[94:95], off offset:-12
	s_waitcnt vmcnt(16)
	s_branch .Lp2_procb_s2

; DI void tok0_mem(ldsp lds, const float* qm, const float* memb, const float* mnw, const float* Wkv, int hm, LAS float* out64, int tid, int wid, int lane) {
;     ...
;             for (int r = 0; r < 4; ++r) {
;                 const int n = wid * 32 + i0 + r; float dd = 0.f, ss = 0.f;
; #pragma unroll
;                 for (int q = 0; q < 4; ++q) { const float4 m = m4[r][q];
;                     dd += m.x * u4[q][0] + m.y * u4[q][1] + m.z * u4[q][2] + m.w * u4[q][3]; ss += m.x * m.x + m.y * m.y + m.z * m.z + m.w * m.w; }
;                 dd = wave_sum(dd); ss = wave_sum(ss);
.Lp2_procb_s2:
	v_mul_f32_e32 v132, v1, v159
	v_mul_f32_e32 v133, v1, v175
	v_mul_f32_e32 v134, v1, v191
	v_mul_f32_e32 v135, v1, v207
	v_mul_f32_e32 v152, v159, v159
	v_mul_f32_e32 v153, v175, v175
	v_mul_f32_e32 v222, v191, v191
	v_mul_f32_e32 v223, v207, v207
	v_fmac_f32_e32 v132, v0, v158
	v_fmac_f32_e32 v133, v0, v174
	v_fmac_f32_e32 v134, v0, v190
	v_fmac_f32_e32 v135, v0, v206
	v_fmac_f32_e32 v152, v158, v158
	v_fmac_f32_e32 v153, v174, v174
	v_fmac_f32_e32 v222, v190, v190
	v_fmac_f32_e32 v223, v206, v206
	v_fmac_f32_e32 v132, v2, v160
	v_fmac_f32_e32 v133, v2, v176
	v_fmac_f32_e32 v134, v2, v192
	v_fmac_f32_e32 v135, v2, v208
	v_fmac_f32_e32 v152, v160, v160
	v_fmac_f32_e32 v153, v176, v176
	v_fmac_f32_e32 v222, v192, v192
	v_fmac_f32_e32 v223, v208, v208
	v_fmac_f32_e32 v132, v3, v161
	v_fmac_f32_e32 v133, v3, v177
	v_fmac_f32_e32 v134, v3, v193
	v_fmac_f32_e32 v135, v3, v209
	v_fmac_f32_e32 v152, v161, v161
	v_fmac_f32_e32 v153, v177, v177
	v_fmac_f32_e32 v222, v193, v193
	v_fmac_f32_e32 v223, v209, v209
	v_add_f32_e32 v124, 0, v132
	v_add_f32_e32 v125, 0, v133
	v_add_f32_e32 v126, 0, v134
	v_add_f32_e32 v127, 0, v135
	v_mov_b32_e32 v128, v152
	v_mov_b32_e32 v129, v153
	v_mov_b32_e32 v130, v222
	v_mov_b32_e32 v131, v223
	v_mul_f32_e32 v132, v5, v163
	v_mul_f32_e32 v133, v5, v179
	v_mul_f32_e32 v134, v5, v195
	v_mul_f32_e32 v135, v5, v211
	v_mul_f32_e32 v152, v163, v163
	v_mul_f32_e32 v153, v179, v179
	v_mul_f32_e32 v222, v195, v195
	v_mul_f32_e32 v223, v211, v211
	v_fmac_f32_e32 v132, v4, v162
	v_fmac_f32_e32 v133, v4, v178
	v_fmac_f32_e32 v134, v4, v194
	v_fmac_f32_e32 v135, v4, v210
	v_fmac_f32_e32 v152, v162, v162
	v_fmac_f32_e32 v153, v178, v178
	v_fmac_f32_e32 v222, v194, v194
	v_fmac_f32_e32 v223, v210, v210
	v_fmac_f32_e32 v132, v6, v164
	v_fmac_f32_e32 v133, v6, v180
	v_fmac_f32_e32 v134, v6, v196
	v_fmac_f32_e32 v135, v6, v212
	v_fmac_f32_e32 v152, v164, v164
	v_fmac_f32_e32 v153, v180, v180
	v_fmac_f32_e32 v222, v196, v196
	v_fmac_f32_e32 v223, v212, v212
	v_fmac_f32_e32 v132, v7, v165
	v_fmac_f32_e32 v133, v7, v181
	v_fmac_f32_e32 v134, v7, v197
	v_fmac_f32_e32 v135, v7, v213
	v_fmac_f32_e32 v152, v165, v165
	v_fmac_f32_e32 v153, v181, v181
	v_fmac_f32_e32 v222, v197, v197
	v_fmac_f32_e32 v223, v213, v213
	v_add_f32_e32 v124, v124, v132
	v_add_f32_e32 v125, v125, v133
	v_add_f32_e32 v126, v126, v134
	v_add_f32_e32 v127, v127, v135
	v_add_f32_e32 v128, v128, v152
	v_add_f32_e32 v129, v129, v153
	v_add_f32_e32 v130, v130, v222
	v_add_f32_e32 v131, v131, v223
	v_mul_f32_e32 v132, v9, v167
	v_mul_f32_e32 v133, v9, v183
	v_mul_f32_e32 v134, v9, v199
	v_mul_f32_e32 v135, v9, v215
	v_mul_f32_e32 v152, v167, v167
	v_mul_f32_e32 v153, v183, v183
	v_mul_f32_e32 v222, v199, v199
	v_mul_f32_e32 v223, v215, v215
	v_fmac_f32_e32 v132, v8, v166
	v_fmac_f32_e32 v133, v8, v182
	v_fmac_f32_e32 v134, v8, v198
	v_fmac_f32_e32 v135, v8, v214
	v_fmac_f32_e32 v152, v166, v166
	v_fmac_f32_e32 v153, v182, v182
	v_fmac_f32_e32 v222, v198, v198
	v_fmac_f32_e32 v223, v214, v214
	v_fmac_f32_e32 v132, v10, v168
	v_fmac_f32_e32 v133, v10, v184
	v_fmac_f32_e32 v134, v10, v200
	v_fmac_f32_e32 v135, v10, v216
	v_fmac_f32_e32 v152, v168, v168
	v_fmac_f32_e32 v153, v184, v184
	v_fmac_f32_e32 v222, v200, v200
	v_fmac_f32_e32 v223, v216, v216
	v_fmac_f32_e32 v132, v11, v169
	v_fmac_f32_e32 v133, v11, v185
	v_fmac_f32_e32 v134, v11, v201
	v_fmac_f32_e32 v135, v11, v217
	v_fmac_f32_e32 v152, v169, v169
	v_fmac_f32_e32 v153, v185, v185
	v_fmac_f32_e32 v222, v201, v201
	v_fmac_f32_e32 v223, v217, v217
	v_add_f32_e32 v124, v124, v132
	v_add_f32_e32 v125, v125, v133
	v_add_f32_e32 v126, v126, v134
	v_add_f32_e32 v127, v127, v135
	v_add_f32_e32 v128, v128, v152
	v_add_f32_e32 v129, v129, v153
	v_add_f32_e32 v130, v130, v222
	v_add_f32_e32 v131, v131, v223
	v_mul_f32_e32 v132, v15, v171
	v_mul_f32_e32 v133, v15, v187
	v_mul_f32_e32 v134, v15, v203
	v_mul_f32_e32 v135, v15, v219
	v_mul_f32_e32 v152, v171, v171
	v_mul_f32_e32 v153, v187, v187
	v_mul_f32_e32 v222, v203, v203
	v_mul_f32_e32 v223, v219, v219
	v_fmac_f32_e32 v132, v14, v170
	v_fmac_f32_e32 v133, v14, v186
	v_fmac_f32_e32 v134, v14, v202
	v_fmac_f32_e32 v135, v14, v218
	v_fmac_f32_e32 v152, v170, v170
	v_fmac_f32_e32 v153, v186, v186
	v_fmac_f32_e32 v222, v202, v202
	v_fmac_f32_e32 v223, v218, v218
	v_fmac_f32_e32 v132, v16, v172
	v_fmac_f32_e32 v133, v16, v188
	v_fmac_f32_e32 v134, v16, v204
	v_fmac_f32_e32 v135, v16, v220
	v_fmac_f32_e32 v152, v172, v172
	v_fmac_f32_e32 v153, v188, v188
	v_fmac_f32_e32 v222, v204, v204
	v_fmac_f32_e32 v223, v220, v220
	v_fmac_f32_e32 v132, v17, v173
	v_fmac_f32_e32 v133, v17, v189
	v_fmac_f32_e32 v134, v17, v205
	v_fmac_f32_e32 v135, v17, v221
	v_fmac_f32_e32 v152, v173, v173
	v_fmac_f32_e32 v153, v189, v189
	v_fmac_f32_e32 v222, v205, v205
	v_fmac_f32_e32 v223, v221, v221
	v_add_f32_e32 v124, v124, v132
	v_add_f32_e32 v125, v125, v133
	v_add_f32_e32 v126, v126, v134
	v_add_f32_e32 v127, v127, v135
	v_add_f32_e32 v128, v128, v152
	v_add_f32_e32 v129, v129, v153
	v_add_f32_e32 v130, v130, v222
	v_add_f32_e32 v131, v131, v223
	ds_bpermute_b32 v132, v97, v124
	ds_bpermute_b32 v133, v97, v125
	ds_bpermute_b32 v134, v97, v126
	ds_bpermute_b32 v135, v97, v127
	ds_bpermute_b32 v152, v97, v128
	ds_bpermute_b32 v153, v97, v129
	ds_bpermute_b32 v222, v97, v130
	ds_bpermute_b32 v223, v97, v131
	s_waitcnt lgkmcnt(7)
	v_add_f32_e32 v124, v124, v132
	s_waitcnt lgkmcnt(6)
	v_add_f32_e32 v125, v125, v133
	s_waitcnt lgkmcnt(5)
	v_add_f32_e32 v126, v126, v134
	s_waitcnt lgkmcnt(4)
	v_add_f32_e32 v127, v127, v135
	s_waitcnt lgkmcnt(3)
; DI float wave_sum(float v) {
; #pragma unroll
;     for (int o = 32; o; o >>= 1) v += __shfl_xor(v, o);
;     return v;
; DI void tok0_mem(ldsp lds, const float* qm, const float* memb, const float* mnw, const float* Wkv, int hm, LAS float* out64, int tid, int wid, int lane) {
;     ...
;                 dd = wave_sum(dd); ss = wave_sum(ss);
;                 if (lane == 0) { const float rstd = rsqrtf(ss * (1.0f / 1024.0f) + 1e-6f); SC[n] = dd * rstd * 0.125f; RSN[n] = rstd; }
;             }
	v_add_f32_e32 v128, v128, v152
	s_waitcnt lgkmcnt(2)
	v_add_f32_e32 v129, v129, v153
	s_waitcnt lgkmcnt(1)
	v_add_f32_e32 v130, v130, v222
	s_waitcnt lgkmcnt(0)
	v_add_f32_e32 v131, v131, v223
	ds_bpermute_b32 v132, v98, v124
	ds_bpermute_b32 v133, v98, v125
	ds_bpermute_b32 v134, v98, v126
	ds_bpermute_b32 v135, v98, v127
	ds_bpermute_b32 v152, v98, v128
	ds_bpermute_b32 v153, v98, v129
	ds_bpermute_b32 v222, v98, v130
	ds_bpermute_b32 v223, v98, v131
	s_waitcnt lgkmcnt(7)
	v_add_f32_e32 v124, v124, v132
	s_waitcnt lgkmcnt(6)
	v_add_f32_e32 v125, v125, v133
	s_waitcnt lgkmcnt(5)
	v_add_f32_e32 v126, v126, v134
	s_waitcnt lgkmcnt(4)
	v_add_f32_e32 v127, v127, v135
	s_waitcnt lgkmcnt(3)
	v_add_f32_e32 v128, v128, v152
	s_waitcnt lgkmcnt(2)
	v_add_f32_e32 v129, v129, v153
	s_waitcnt lgkmcnt(1)
	v_add_f32_e32 v130, v130, v222
	s_waitcnt lgkmcnt(0)
	v_add_f32_e32 v131, v131, v223
	ds_bpermute_b32 v132, v99, v124
	ds_bpermute_b32 v133, v99, v125
	ds_bpermute_b32 v134, v99, v126
	ds_bpermute_b32 v135, v99, v127
	ds_bpermute_b32 v152, v99, v128
	ds_bpermute_b32 v153, v99, v129
	ds_bpermute_b32 v222, v99, v130
	ds_bpermute_b32 v223, v99, v131
	s_waitcnt lgkmcnt(7)
	v_add_f32_e32 v124, v124, v132
	s_waitcnt lgkmcnt(6)
	v_add_f32_e32 v125, v125, v133
	s_waitcnt lgkmcnt(5)
	v_add_f32_e32 v126, v126, v134
	s_waitcnt lgkmcnt(4)
	v_add_f32_e32 v127, v127, v135
	s_waitcnt lgkmcnt(3)
	v_add_f32_e32 v128, v128, v152
	s_waitcnt lgkmcnt(2)
	v_add_f32_e32 v129, v129, v153
	s_waitcnt lgkmcnt(1)
	v_add_f32_e32 v130, v130, v222
	s_waitcnt lgkmcnt(0)
	v_add_f32_e32 v131, v131, v223
	ds_bpermute_b32 v132, v100, v124
	ds_bpermute_b32 v133, v100, v125
	ds_bpermute_b32 v134, v100, v126
	ds_bpermute_b32 v135, v100, v127
	ds_bpermute_b32 v152, v100, v128
	ds_bpermute_b32 v153, v100, v129
	ds_bpermute_b32 v222, v100, v130
	ds_bpermute_b32 v223, v100, v131
	s_waitcnt lgkmcnt(7)
	v_add_f32_e32 v124, v124, v132
	s_waitcnt lgkmcnt(6)
	v_add_f32_e32 v125, v125, v133
	s_waitcnt lgkmcnt(5)
	v_add_f32_e32 v126, v126, v134
	s_waitcnt lgkmcnt(4)
	v_add_f32_e32 v127, v127, v135
	s_waitcnt lgkmcnt(3)
	v_add_f32_e32 v128, v128, v152
	s_waitcnt lgkmcnt(2)
	v_add_f32_e32 v129, v129, v153
	s_waitcnt lgkmcnt(1)
	v_add_f32_e32 v130, v130, v222
	s_waitcnt lgkmcnt(0)
	v_add_f32_e32 v131, v131, v223
	ds_bpermute_b32 v132, v101, v124
	ds_bpermute_b32 v133, v101, v125
	ds_bpermute_b32 v134, v101, v126
	ds_bpermute_b32 v135, v101, v127
	ds_bpermute_b32 v152, v101, v128
	ds_bpermute_b32 v153, v101, v129
	ds_bpermute_b32 v222, v101, v130
	ds_bpermute_b32 v223, v101, v131
	s_waitcnt lgkmcnt(7)
	v_add_f32_e32 v124, v124, v132
	s_waitcnt lgkmcnt(6)
	v_add_f32_e32 v125, v125, v133
	s_waitcnt lgkmcnt(5)
	v_add_f32_e32 v126, v126, v134
	s_waitcnt lgkmcnt(4)
	v_add_f32_e32 v127, v127, v135
	s_waitcnt lgkmcnt(3)
	v_add_f32_e32 v128, v128, v152
	s_waitcnt lgkmcnt(2)
	v_add_f32_e32 v129, v129, v153
	s_waitcnt lgkmcnt(1)
	v_add_f32_e32 v130, v130, v222
	s_waitcnt lgkmcnt(0)
	v_add_f32_e32 v131, v131, v223
	ds_bpermute_b32 v132, v102, v124
	ds_bpermute_b32 v133, v102, v125
	ds_bpermute_b32 v134, v102, v126
	ds_bpermute_b32 v135, v102, v127
	ds_bpermute_b32 v152, v102, v128
	ds_bpermute_b32 v153, v102, v129
	ds_bpermute_b32 v222, v102, v130
	ds_bpermute_b32 v223, v102, v131
	s_waitcnt lgkmcnt(7)
	v_add_f32_e32 v124, v124, v132
	s_waitcnt lgkmcnt(6)
	v_add_f32_e32 v125, v125, v133
	s_waitcnt lgkmcnt(5)
	v_add_f32_e32 v126, v126, v134
	s_waitcnt lgkmcnt(4)
	v_add_f32_e32 v127, v127, v135
	s_waitcnt lgkmcnt(3)
	v_add_f32_e32 v128, v128, v152
	s_waitcnt lgkmcnt(2)
	v_add_f32_e32 v129, v129, v153
	s_waitcnt lgkmcnt(1)
	v_add_f32_e32 v130, v130, v222
	s_waitcnt lgkmcnt(0)
	v_add_f32_e32 v131, v131, v223
	s_and_saveexec_b64 s[22:23], s[40:41]
	v_fmamk_f32 v128, v128, 0x3a800000, v231
	v_mul_f32_e32 v132, 0x4b800000, v128
	v_cmp_gt_f32_e32 vcc, s33, v128
	s_nop 1
	v_cndmask_b32_e32 v128, v128, v132, vcc
	v_rsq_f32_e32 v128, v128
	s_nop 0
	v_mul_f32_e32 v132, 0x45800000, v128
	v_cndmask_b32_e32 v132, v128, v132, vcc
	v_mul_f32_e32 v124, v124, v132
	v_mul_f32_e32 v124, 0x3e000000, v124
	v_add_u32_e64 v152, 16, s30
	ds_write2st64_b32 v152, v124, v132 offset1:4
	v_fmamk_f32 v129, v129, 0x3a800000, v231
	v_mul_f32_e32 v133, 0x4b800000, v129
	v_cmp_gt_f32_e32 vcc, s33, v129
	s_nop 1
	v_cndmask_b32_e32 v129, v129, v133, vcc
	v_rsq_f32_e32 v129, v129
	s_nop 0
	v_mul_f32_e32 v133, 0x45800000, v129
	v_cndmask_b32_e32 v133, v129, v133, vcc
	v_mul_f32_e32 v125, v125, v133
	v_mul_f32_e32 v125, 0x3e000000, v125
	v_add_u32_e64 v153, 20, s30
	ds_write2st64_b32 v153, v125, v133 offset1:4
	v_fmamk_f32 v130, v130, 0x3a800000, v231
	v_mul_f32_e32 v134, 0x4b800000, v130
	v_cmp_gt_f32_e32 vcc, s33, v130
	s_nop 1
	v_cndmask_b32_e32 v130, v130, v134, vcc
	v_rsq_f32_e32 v130, v130
	s_nop 0
	v_mul_f32_e32 v134, 0x45800000, v130
	v_cndmask_b32_e32 v134, v130, v134, vcc
	v_mul_f32_e32 v126, v126, v134
	v_mul_f32_e32 v126, 0x3e000000, v126
	v_add_u32_e64 v222, 24, s30
	ds_write2st64_b32 v222, v126, v134 offset1:4
	v_fmamk_f32 v131, v131, 0x3a800000, v231
	v_mul_f32_e32 v135, 0x4b800000, v131
	v_cmp_gt_f32_e32 vcc, s33, v131
	s_nop 1
	v_cndmask_b32_e32 v131, v131, v135, vcc
	v_rsq_f32_e32 v131, v131
	s_nop 0
	v_mul_f32_e32 v135, 0x45800000, v131
	v_cndmask_b32_e32 v135, v131, v135, vcc
	v_mul_f32_e32 v127, v127, v135
	v_mul_f32_e32 v127, 0x3e000000, v127
	v_add_u32_e64 v223, 28, s30
	ds_write2st64_b32 v223, v127, v135 offset1:4
	s_or_b64 exec, exec, s[22:23]
	s_add_i32 s0, s0, 8
	s_add_i32 s30, s30, 32
	s_cmp_gt_u32 s0, 27
	s_cbranch_scc0 .LBB0_834
	s_branch .LBB0_842
